# HGRN2 phase-a chunks: second value piece loaded at the chunk top with the other operand pieces
# baseline (speedup 1.0000x reference)
.LBB0_911:
	s_mov_b64 s[10:11], s[58:59]
	s_load_dwordx2 s[14:15], s[10:11], 0x158
	s_mov_b64 s[10:11], s[58:59]
	s_mov_b64 s[12:13], s[58:59]
	s_load_dwordx2 s[10:11], s[10:11], 0x158
	s_and_b32 s19, s8, 0xfffff800
	s_and_b32 s20, s16, 0x7c0
	s_load_dwordx2 s[12:13], s[12:13], 0x158
	v_mbcnt_lo_u32_b32 v16, -1, 0
	v_mbcnt_hi_u32_b32 v16, -1, v16
	s_or_b32 s19, s19, s20
	v_add_u32_e32 v17, s61, v16
	s_bfe_u32 s20, s18, 0x20005
	v_lshlrev_b32_e32 v38, 3, v17
	s_lshl_b32 s21, s20, 8
	v_and_b32_e32 v18, 0x78, v38
	s_waitcnt lgkmcnt(0)
	s_add_u32 s14, s14, s21
	s_addc_u32 s15, s15, 0
	v_lshlrev_b32_e32 v156, 1, v18
	v_lshl_add_u64 v[0:1], s[14:15], 0, v[156:157]
	v_ashrrev_i32_e32 v21, 4, v17
	v_lshl_add_u64 v[0:1], v[0:1], 0, s[46:47]
	v_add_u32_e32 v2, s19, v21
	v_mad_i64_i32 v[2:3], s[14:15], v2, s83, v[0:1]
	v_add_co_u32_e32 v14, vcc, s72, v2
	v_add_u32_e32 v2, 0x200, v17
	s_nop 0
	v_addc_co_u32_e32 v15, vcc, 0, v3, vcc
	global_load_dwordx4 v[10:13], v[14:15], off
	v_ashrrev_i32_e32 v39, 4, v2
	s_lshl_b32 s14, s20, 9
	v_add_u32_e32 v2, s19, v39
	v_lshlrev_b32_e32 v3, 2, v18
	s_add_i32 s14, s14, 0
	v_add_u32_e32 v40, s43, v3
	v_add_u32_e32 v3, s14, v3
	v_mad_i64_i32 v[8:9], s[14:15], v2, s83, v[0:1]
	v_add_u32_e32 v34, 0x22400, v3
	v_add_co_u32_e32 v8, vcc, s72, v8
	ds_read_b128 v[4:7], v34
	ds_read_b128 v[0:3], v34 offset:16
	v_addc_co_u32_e32 v9, vcc, 0, v9, vcc
	global_load_dwordx4 v[22:25], v[14:15], off offset:1024
	global_load_dwordx4 v[26:29], v[8:9], off
	global_load_dwordx4 v[70:73], v[8:9], off offset:1024
	s_waitcnt lgkmcnt(0)
	v_sub_f32_e32 v20, 1.0, v6
	v_sub_f32_e32 v31, 1.0, v0
	v_sub_f32_e32 v32, 1.0, v1
	v_sub_f32_e32 v14, 1.0, v4
	v_sub_f32_e32 v15, 1.0, v5
	v_sub_f32_e32 v30, 1.0, v7
	v_sub_f32_e32 v33, 1.0, v2
	s_add_i32 s14, 0, 0x1fc00
	s_waitcnt vmcnt(0)
	v_lshlrev_b32_e32 v19, 16, v10
	v_lshlrev_b32_e32 v35, 16, v11
	v_lshlrev_b32_e32 v36, 16, v12
	v_and_b32_e32 v12, 0xffff0000, v12
	v_lshlrev_b32_e32 v37, 16, v13
	v_mul_f32_e32 v19, 0xbfb8aa3b, v19
	v_mul_f32_e32 v35, 0xbfb8aa3b, v35
	v_mul_f32_e32 v36, 0xbfb8aa3b, v36
	v_mul_f32_e32 v12, 0xbfb8aa3b, v12
	v_mul_f32_e32 v37, 0xbfb8aa3b, v37
	v_exp_f32_e32 v19, v19
	v_exp_f32_e32 v35, v35
	v_exp_f32_e32 v36, v36
	v_exp_f32_e32 v12, v12
	v_exp_f32_e32 v37, v37
	v_and_b32_e32 v10, 0xffff0000, v10
	v_and_b32_e32 v11, 0xffff0000, v11
	v_and_b32_e32 v13, 0xffff0000, v13
	v_mul_f32_e32 v10, 0xbfb8aa3b, v10
	v_mul_f32_e32 v11, 0xbfb8aa3b, v11
	v_mul_f32_e32 v13, 0xbfb8aa3b, v13
	v_exp_f32_e32 v10, v10
	v_exp_f32_e32 v11, v11
	v_exp_f32_e32 v41, v13
	v_add_f32_e32 v13, 1.0, v19
	v_add_f32_e32 v19, 1.0, v35
	v_add_f32_e32 v35, 1.0, v36
	v_add_f32_e32 v12, 1.0, v12
	v_add_f32_e32 v36, 1.0, v37
	v_rcp_f32_e32 v37, v19
	v_rcp_f32_e32 v35, v35
	v_rcp_f32_e32 v12, v12
	v_rcp_f32_e32 v13, v13
	v_add_f32_e32 v10, 1.0, v10
	v_add_f32_e32 v11, 1.0, v11
	v_rcp_f32_e32 v10, v10
	v_rcp_f32_e32 v11, v11
	v_rcp_f32_e32 v36, v36
	v_fma_f32 v6, v20, v37, v6
	v_fma_f32 v20, v35, v31, v0
	v_fma_f32 v0, v12, v32, v1
	v_add_f32_e32 v1, 1.0, v41
	v_fma_f32 v19, v14, v13, v4
	v_rcp_f32_e32 v4, v1
	v_fma_f32 v5, v15, v10, v5
	v_fmac_f32_e32 v7, v30, v11
	v_fma_f32 v1, v36, v33, v2
	v_sub_f32_e32 v2, 1.0, v3
	v_log_f32_e32 v10, v19
	v_log_f32_e32 v11, v5
	v_log_f32_e32 v12, v6
	v_log_f32_e32 v13, v7
	v_fmac_f32_e32 v3, v4, v2
	v_log_f32_e32 v14, v20
	v_log_f32_e32 v30, v1
	v_log_f32_e32 v31, v3
	v_log_f32_e32 v15, v0
	v_lshlrev_b32_e32 v2, 9, v21
	v_pk_mul_f32 v[12:13], v[12:13], s[70:71] op_sel_hi:[1,0]
	v_pk_mul_f32 v[10:11], v[10:11], s[70:71] op_sel_hi:[1,0]
	v_add_u32_e32 v4, v40, v2
	v_pk_mul_f32 v[32:33], v[30:31], s[70:71] op_sel_hi:[1,0]
	v_pk_mul_f32 v[30:31], v[14:15], s[70:71] op_sel_hi:[1,0]
	ds_write_b128 v4, v[10:13]
	ds_write_b128 v4, v[30:33] offset:16
	v_bitop3_b32 v2, v21, 56, v38 bitop3:0x48
	v_lshlrev_b32_e32 v10, 1, v21
	v_lshlrev_b32_e32 v2, 1, v2
	v_and_b32_e32 v10, 14, v10
	v_add3_u32 v2, 0, v2, v10
	v_mad_u32_u24 v10, v18, s85, v2
	ds_write_b16 v10, v22 offset:44032
	ds_write_b16_d16_hi v10, v22 offset:44176
	ds_write_b16 v10, v23 offset:44320
	ds_write_b16_d16_hi v10, v23 offset:44464
	ds_write_b16 v10, v24 offset:44608
	ds_write_b16_d16_hi v10, v24 offset:44752
	ds_write_b16 v10, v25 offset:44896
	ds_write_b16_d16_hi v10, v25 offset:45040
	v_mov_b32_e32 v30, v70
	v_mov_b32_e32 v31, v71
	v_mov_b32_e32 v32, v72
	v_mov_b32_e32 v33, v73
	v_lshlrev_b32_e32 v8, 16, v26
	v_mul_f32_e32 v8, 0xbfb8aa3b, v8
	v_exp_f32_e32 v24, v8
	v_and_b32_e32 v21, 0xffff0000, v26
	ds_read_b128 v[12:15], v34
	ds_read_b128 v[8:11], v34 offset:16
	v_mul_f32_e32 v21, 0xbfb8aa3b, v21
	v_add_f32_e32 v24, 1.0, v24
	v_rcp_f32_e32 v24, v24
	v_exp_f32_e32 v25, v21
	v_lshlrev_b32_e32 v22, 16, v27
	s_waitcnt lgkmcnt(1)
	v_sub_f32_e32 v21, 1.0, v12
	v_fma_f32 v21, v24, v21, v12
	v_add_f32_e32 v12, 1.0, v25
	v_mul_f32_e32 v22, 0xbfb8aa3b, v22
	v_rcp_f32_e32 v12, v12
	v_exp_f32_e32 v26, v22
	v_and_b32_e32 v23, 0xffff0000, v27
	v_sub_f32_e32 v22, 1.0, v13
	v_fma_f32 v22, v12, v22, v13
	v_add_f32_e32 v12, 1.0, v26
	v_mul_f32_e32 v13, 0xbfb8aa3b, v23
	v_rcp_f32_e32 v12, v12
	v_exp_f32_e32 v13, v13
	v_lshlrev_b32_e32 v27, 16, v28
	v_sub_f32_e32 v23, 1.0, v14
	v_fma_f32 v12, v12, v23, v14
	v_add_f32_e32 v13, 1.0, v13
	v_mul_f32_e32 v14, 0xbfb8aa3b, v27
	v_rcp_f32_e32 v13, v13
	v_exp_f32_e32 v14, v14
	v_and_b32_e32 v28, 0xffff0000, v28
	v_sub_f32_e32 v23, 1.0, v15
	v_fmac_f32_e32 v15, v13, v23
	v_add_f32_e32 v13, 1.0, v14
	v_mul_f32_e32 v14, 0xbfb8aa3b, v28
	v_rcp_f32_e32 v13, v13
	v_exp_f32_e32 v14, v14
	s_waitcnt lgkmcnt(0)
	v_sub_f32_e32 v23, 1.0, v8
	v_lshlrev_b32_e32 v35, 16, v29
	v_fma_f32 v8, v13, v23, v8
	v_add_f32_e32 v13, 1.0, v14
	v_rcp_f32_e32 v13, v13
	v_and_b32_e32 v29, 0xffff0000, v29
	v_sub_f32_e32 v14, 1.0, v9
	v_mul_f32_e32 v23, 0xbfb8aa3b, v35
	v_exp_f32_e32 v23, v23
	v_fma_f32 v9, v13, v14, v9
	v_mul_f32_e32 v13, 0xbfb8aa3b, v29
	v_exp_f32_e32 v13, v13
	v_add_f32_e32 v14, 1.0, v23
	v_rcp_f32_e32 v14, v14
	v_sub_f32_e32 v23, 1.0, v10
	v_add_f32_e32 v13, 1.0, v13
	v_rcp_f32_e32 v13, v13
	v_fma_f32 v10, v14, v23, v10
	v_sub_f32_e32 v14, 1.0, v11
	v_log_f32_e32 v24, v21
	v_log_f32_e32 v25, v22
	v_log_f32_e32 v26, v12
	v_log_f32_e32 v27, v15
	v_fmac_f32_e32 v11, v13, v14
	v_lshlrev_b32_e32 v13, 9, v39
	v_log_f32_e32 v28, v8
	v_log_f32_e32 v34, v10
	v_log_f32_e32 v35, v11
	v_log_f32_e32 v29, v9
	v_add_u32_e32 v14, v40, v13
	v_bitop3_b32 v13, v39, 56, v38 bitop3:0x48
	v_lshlrev_b32_e32 v23, 1, v39
	v_lshlrev_b32_e32 v13, 1, v13
	v_and_b32_e32 v23, 14, v23
	v_add3_u32 v13, 0, v13, v23
	v_pk_mul_f32 v[26:27], v[26:27], s[70:71] op_sel_hi:[1,0]
	v_pk_mul_f32 v[24:25], v[24:25], s[70:71] op_sel_hi:[1,0]
	v_mad_u32_u24 v23, v18, s85, v13
	v_pk_mul_f32 v[36:37], v[34:35], s[70:71] op_sel_hi:[1,0]
	v_pk_mul_f32 v[34:35], v[28:29], s[70:71] op_sel_hi:[1,0]
	ds_write_b128 v14, v[24:27]
	ds_write_b128 v14, v[34:37] offset:16
	s_waitcnt vmcnt(0)
	ds_write_b16 v23, v30 offset:44032
	ds_write_b16_d16_hi v23, v30 offset:44176
	ds_write_b16 v23, v31 offset:44320
	ds_write_b16_d16_hi v23, v31 offset:44464
	ds_write_b16 v23, v32 offset:44608
	ds_write_b16_d16_hi v23, v32 offset:44752
	ds_write_b16 v23, v33 offset:44896
	ds_write_b16_d16_hi v23, v33 offset:45040
	v_and_b32_e32 v23, 0x7f, v17
	v_ashrrev_i32_e32 v41, 7, v17
	v_lshlrev_b32_e32 v24, 13, v41
	v_lshlrev_b32_e32 v48, 2, v23
	v_add3_u32 v23, s43, v24, v48
	s_waitcnt lgkmcnt(0)
	s_barrier
	ds_read2st64_b32 v[26:27], v23 offset1:2
	ds_read2st64_b32 v[28:29], v23 offset0:4 offset1:6
	ds_read2st64_b32 v[30:31], v23 offset0:8 offset1:10
	ds_read2st64_b32 v[34:35], v23 offset0:12 offset1:14
	ds_read2st64_b32 v[36:37], v23 offset0:16 offset1:18
	s_waitcnt lgkmcnt(4)
	v_add_f32_e32 v25, 0, v26
	v_add_f32_e32 v27, v25, v27
	s_waitcnt lgkmcnt(3)
	v_add_f32_e32 v26, v27, v28
	v_add_f32_e32 v29, v26, v29
	s_waitcnt lgkmcnt(2)
	v_add_f32_e32 v28, v29, v30
	v_add_f32_e32 v32, v28, v31
	ds_read2st64_b32 v[42:43], v23 offset0:20 offset1:22
	s_waitcnt lgkmcnt(2)
	v_add_f32_e32 v30, v32, v34
	v_add_f32_e32 v31, v30, v35
	ds_read2st64_b32 v[44:45], v23 offset0:24 offset1:26
	s_waitcnt lgkmcnt(2)
	v_add_f32_e32 v33, v31, v36
	v_add_f32_e32 v34, v33, v37
	ds_read2st64_b32 v[46:47], v23 offset0:28 offset1:30
	s_waitcnt lgkmcnt(2)
	v_add_f32_e32 v39, v34, v42
	v_add_f32_e32 v40, v39, v43
	s_waitcnt lgkmcnt(1)
	v_add_f32_e32 v37, v40, v44
	v_add_f32_e32 v38, v37, v45
	s_waitcnt lgkmcnt(0)
	v_add_f32_e32 v35, v38, v46
	v_add_f32_e32 v36, v35, v47
	v_lshl_add_u32 v42, v17, 2, s14
	v_mov_b32_e32 v24, 0
	ds_write_b32 v42, v36
	v_add_u32_e32 v42, s14, v48
	v_cmp_lt_i32_e32 vcc, 0, v41
	s_waitcnt lgkmcnt(0)
	s_barrier
	s_and_saveexec_b64 s[14:15], vcc
	s_cbranch_execz .LBB0_917
	ds_read_b32 v24, v42
	s_waitcnt lgkmcnt(0)
	v_add_f32_e32 v24, 0, v24
	s_or_b64 exec, exec, s[14:15]
	v_cmp_lt_i32_e32 vcc, 1, v41
	s_and_saveexec_b64 s[14:15], vcc
	s_cbranch_execnz .LBB0_918
